# v27 plus code placement: one s_nop before and after the diff loop so both attention loop heads sit at 0 mod 8 bytes
# baseline (speedup 1.0000x reference)
; template <int DQK, bool ALIBI>
; DI void attn_pass(const u16* __restrict__ Qp, int ldq, const u16* __restrict__ Kp, int ldk, const u16* __restrict__ VTp,
;                   int seq_start, int kt_lo, int kt_hi, int q0, float slope2, f32x16 (&O)[4], float& lsum, char* lds) {
;     ...
;   bf16x8 qf[NKS];
;   const u16* qrow = Qp + (size_t)(seq_start + q0 + w * 32 + r) * ldq;
; #pragma unroll
;   for (int ks = 0; ks < NKS; ++ks) qf[ks] = *(const bf16x8*)(qrow + ks * 16 + h * 8);
; #pragma unroll
;   for (int db = 0; db < 4; ++db)
; #pragma unroll
;     for (int e = 0; e < 16; ++e) O[db][e] = 0.f;
;   f32x2 l2 = {0.f, 0.f};
;   const int qw0 = q0 + w * 32;
;   const float qpos = (float)(qw0 + r - 4 * h);
;   u32x4 rk[KPT], rv[2];
;     ...
;   __syncthreads();
;   ATT_GLOAD(kt_lo);
;   ATT_LSTORE(0);
;   if (kt_lo + 1 < kt_hi) ATT_GLOAD(kt_lo + 1);
;   __syncthreads();
.LBB0_1147:
	v_mov_b32_e32 v143, 0
	s_xor_b64 s[60:61], s[44:45], -1
	v_lshlrev_b32_e32 v153, 3, v72
	s_andn2_b64 vcc, exec, s[56:57]
	v_mov_b32_e32 v142, v143
	v_mov_b32_e32 v65, v143
	v_mov_b32_e32 v64, v143
	v_mov_b32_e32 v63, v143
	v_mov_b32_e32 v62, v143
	v_mov_b32_e32 v61, v143
	v_mov_b32_e32 v60, v143
	v_mov_b32_e32 v59, v143
	v_mov_b32_e32 v58, v143
	v_mov_b32_e32 v57, v143
	v_mov_b32_e32 v56, v143
	v_mov_b32_e32 v55, v143
	v_mov_b32_e32 v54, v143
	v_mov_b32_e32 v53, v143
	v_mov_b32_e32 v52, v143
	v_mov_b32_e32 v51, v143
	v_mov_b32_e32 v50, v143
	v_mov_b32_e32 v49, v143
	v_mov_b32_e32 v48, v143
	v_mov_b32_e32 v47, v143
	v_mov_b32_e32 v46, v143
	v_mov_b32_e32 v45, v143
	v_mov_b32_e32 v44, v143
	v_mov_b32_e32 v43, v143
	v_mov_b32_e32 v42, v143
	v_mov_b32_e32 v41, v143
	v_mov_b32_e32 v40, v143
	v_mov_b32_e32 v39, v143
	v_mov_b32_e32 v38, v143
	v_mov_b32_e32 v37, v143
	v_mov_b32_e32 v36, v143
	v_mov_b32_e32 v35, v143
	v_mov_b32_e32 v34, v143
	v_mov_b32_e32 v33, v143
	v_mov_b32_e32 v32, v143
	v_mov_b32_e32 v31, v143
	v_mov_b32_e32 v30, v143
	v_mov_b32_e32 v29, v143
	v_mov_b32_e32 v28, v143
	v_mov_b32_e32 v27, v143
	v_mov_b32_e32 v26, v143
	v_mov_b32_e32 v25, v143
	v_mov_b32_e32 v24, v143
	v_mov_b32_e32 v23, v143
	v_mov_b32_e32 v22, v143
	v_mov_b32_e32 v21, v143
	v_mov_b32_e32 v20, v143
	v_mov_b32_e32 v19, v143
	v_mov_b32_e32 v18, v143
	v_mov_b32_e32 v17, v143
	v_mov_b32_e32 v16, v143
	v_mov_b32_e32 v15, v143
	v_mov_b32_e32 v14, v143
	v_mov_b32_e32 v13, v143
	v_mov_b32_e32 v12, v143
	v_mov_b32_e32 v11, v143
	v_mov_b32_e32 v10, v143
	v_mov_b32_e32 v9, v143
	v_mov_b32_e32 v8, v143
	v_mov_b32_e32 v7, v143
	v_mov_b32_e32 v6, v143
	v_mov_b32_e32 v5, v143
	v_mov_b32_e32 v4, v143
	v_mov_b32_e32 v3, v143
	v_mov_b32_e32 v2, v143
	s_waitcnt lgkmcnt(0)
	s_barrier
	s_cbranch_vccnz .LBB0_1163
	v_or_b32_e32 v2, v129, v71
	v_lshlrev_b32_e32 v3, 2, v72
	v_sub_u32_e32 v2, v2, v3
	v_cvt_f32_i32_e32 v154, v2
	v_add_u32_e32 v2, v70, v73
	v_ashrrev_i32_e32 v4, 3, v2
	v_and_b32_e32 v2, -8, v2
	v_sub_u32_e32 v2, v70, v2
	v_lshlrev_b32_e32 v158, 4, v2
	v_lshlrev_b32_e32 v2, 3, v2
	v_ashrrev_i32_e32 v3, 31, v2
	v_lshl_add_u64 v[136:137], v[2:3], 1, s[6:7]
	v_and_b32_e32 v2, 7, v70
	v_lshlrev_b32_e32 v2, 4, v2
	v_mov_b32_e32 v3, v1
	v_mul_lo_u32 v157, v4, s16
	v_add_u32_e32 v159, s86, v4
	v_lshl_add_u64 v[4:5], v[68:69], 0, v[2:3]
	v_lshl_add_u64 v[2:3], v[66:67], 0, v[2:3]
	v_lshl_add_u64 v[140:141], s[58:59], 0, v[2:3]
	v_mov_b32_e32 v2, 0
	v_or_b32_e32 v155, 31, v129
	v_mul_u32_u24_e32 v156, 0x90, v71
	v_lshl_add_u64 v[138:139], s[58:59], 0, v[4:5]
	s_mov_b32 s87, 0
	s_mov_b32 s89, s83
	v_mov_b32_e32 v3, v2
	v_mov_b32_e32 v4, v2
	v_mov_b32_e32 v5, v2
	v_mov_b32_e32 v6, v2
	v_mov_b32_e32 v7, v2
	v_mov_b32_e32 v8, v2
	v_mov_b32_e32 v9, v2
	v_mov_b32_e32 v10, v2
	v_mov_b32_e32 v11, v2
	v_mov_b32_e32 v12, v2
	v_mov_b32_e32 v13, v2
	v_mov_b32_e32 v14, v2
	v_mov_b32_e32 v15, v2
	v_mov_b32_e32 v16, v2
	v_mov_b32_e32 v17, v2
	v_mov_b32_e32 v18, v2
	v_mov_b32_e32 v19, v2
	v_mov_b32_e32 v20, v2
	v_mov_b32_e32 v21, v2
	v_mov_b32_e32 v22, v2
	v_mov_b32_e32 v23, v2
	v_mov_b32_e32 v24, v2
	v_mov_b32_e32 v25, v2
	v_mov_b32_e32 v26, v2
	v_mov_b32_e32 v27, v2
	v_mov_b32_e32 v28, v2
	v_mov_b32_e32 v29, v2
	v_mov_b32_e32 v30, v2
	v_mov_b32_e32 v31, v2
	v_mov_b32_e32 v32, v2
	v_mov_b32_e32 v33, v2
	v_mov_b32_e32 v34, v2
	v_mov_b32_e32 v35, v2
	v_mov_b32_e32 v36, v2
	v_mov_b32_e32 v37, v2
	v_mov_b32_e32 v38, v2
	v_mov_b32_e32 v39, v2
	v_mov_b32_e32 v40, v2
	v_mov_b32_e32 v41, v2
	v_mov_b32_e32 v42, v2
	v_mov_b32_e32 v43, v2
	v_mov_b32_e32 v44, v2
	v_mov_b32_e32 v45, v2
	v_mov_b32_e32 v46, v2
	v_mov_b32_e32 v47, v2
	v_mov_b32_e32 v48, v2
	v_mov_b32_e32 v49, v2
	v_mov_b32_e32 v50, v2
	v_mov_b32_e32 v51, v2
	v_mov_b32_e32 v52, v2
	v_mov_b32_e32 v53, v2
	v_mov_b32_e32 v54, v2
	v_mov_b32_e32 v55, v2
	v_mov_b32_e32 v56, v2
	v_mov_b32_e32 v57, v2
	v_mov_b32_e32 v58, v2
	v_mov_b32_e32 v59, v2
	v_mov_b32_e32 v60, v2
	v_mov_b32_e32 v61, v2
	v_mov_b32_e32 v62, v2
	v_mov_b32_e32 v63, v2
	v_mov_b32_e32 v64, v2
	v_mov_b32_e32 v65, v2
	v_mov_b32_e32 v142, v2
	v_mov_b32_e32 v143, v2
	s_nop 0

; #define MFMA(a, b, c) __builtin_amdgcn_mfma_f32_32x32x16_bf16((a), (b), (c), 0, 0, 0)
; template <int DQK, bool ALIBI>
; DI void attn_pass(const u16* __restrict__ Qp, int ldq, const u16* __restrict__ Kp, int ldk, const u16* __restrict__ VTp,
;                   int seq_start, int kt_lo, int kt_hi, int q0, float slope2, f32x16 (&O)[4], float& lsum, char* lds) {
;     ...
; #pragma unroll
;     for (int s = 0; s < 2; ++s)
; #pragma unroll
;       for (int db = 0; db < 4; ++db) O[db] = MFMA(vg[s][db], pg[s], O[db]);
;     __syncthreads();
.Lmy_dif_g2:
	s_add_i32 s87, s87, 1
	s_add_i32 s6, s73, s87
	v_lshl_add_u64 v[138:139], v[138:139], 0, s[80:81]
	v_lshl_add_u64 v[140:141], v[140:141], 0, s[80:81]
	s_cmp_lt_i32 s6, s77
	v_mfma_f32_32x32x16_bf16 v[18:33], v[90:93], v[66:69], v[18:33]
	v_mfma_f32_32x32x16_bf16 v[2:17], v[94:97], v[66:69], v[2:17]
	v_mfma_f32_32x32x16_bf16 v[50:65], v[160:163], v[70:73], v[50:65]
	s_waitcnt lgkmcnt(0)
	s_barrier
	v_mfma_f32_32x32x16_bf16 v[34:49], v[164:167], v[70:73], v[34:49]
	v_mfma_f32_32x32x16_bf16 v[18:33], v[168:171], v[70:73], v[18:33]
	v_mfma_f32_32x32x16_bf16 v[2:17], v[82:85], v[70:73], v[2:17]
	s_cbranch_scc0 .LBB0_1163
	s_mov_b32 s89, s88
	s_branch .LBB0_1149
	s_nop 0
